# pb2 + DFT stage 2: each unit's H rows touched into L2 at unit start (4 / 2 dword loads per wave)
# speedup vs baseline: 1.0071x; 1.0071x over previous
.LBB0_669:
	s_andn2_b64 vcc, exec, s[0:1]
	s_cbranch_vccnz .LBB0_784
	s_cmpk_gt_i32 s40, 0x41f
	s_mulk_i32 s41, 0x2200
	s_cbranch_scc0 .LBB0_675
	s_add_i32 s0, s40, 0xfffffbe0
	s_lshr_b32 s1, s0, 3
	s_mul_hi_u32 s0, s0, 0x3e0f83e1
	s_mul_hi_u32 s4, s1, 0x1f07c1f1
	s_lshl_b32 s0, s0, 6
	s_lshr_b32 s4, s4, 2
	s_and_b32 s0, s0, 0xfffff000
	s_mul_i32 s4, s4, 33
	s_addk_i32 s0, 0x4000
	s_bfe_u32 s15, s18, 0x30006
	s_sub_i32 s14, s1, s4
	s_ashr_i32 s1, s0, 31
	s_lshl_b64 s[10:11], s[0:1], 11
	s_lshl_b32 s4, s14, 17
	s_lshl_b32 s1, s15, 6
	v_readlane_b32 s5, v254, 17
	s_add_u32 s5, s5, s10
	v_readlane_b32 s6, v254, 18
	v_mov_b32_e32 v212, v210
	s_addc_u32 s10, s6, s11
	s_add_u32 s4, s5, s4
	v_ashrrev_i32_e32 v211, 4, v212
	s_addc_u32 s5, s10, 0
	s_lshl_b32 s10, s15, 7
	v_lshlrev_b32_e32 v150, 3, v211
	v_and_b32_e32 v149, 15, v212
	s_add_u32 s10, s4, s10
	s_waitcnt vmcnt(1)
	v_or_b32_e32 v4, 1, v150
	s_addc_u32 s11, s5, 0
	v_lshlrev_b32_e32 v98, 3, v149
	v_ashrrev_i32_e32 v151, 31, v150
	v_ashrrev_i32_e32 v5, 31, v4
	s_waitcnt vmcnt(0)
	v_or_b32_e32 v6, 2, v150
	v_or_b32_e32 v8, 3, v150
	v_lshl_add_u64 v[152:153], s[10:11], 0, v[98:99]
	v_lshlrev_b32_e32 v231, 10, v210
	global_load_dword v197, v231, s[10:11]
	v_add_u32_e32 v231, 0x10000, v231
	global_load_dword v197, v231, s[10:11]
	v_lshlrev_b64 v[2:3], 10, v[150:151]
	v_lshlrev_b64 v[4:5], 10, v[4:5]
	v_ashrrev_i32_e32 v7, 31, v6
	v_ashrrev_i32_e32 v9, 31, v8
	v_lshl_add_u64 v[2:3], v[152:153], 0, v[2:3]
	v_lshl_add_u64 v[4:5], v[152:153], 0, v[4:5]
	v_lshlrev_b64 v[6:7], 10, v[6:7]
	v_lshlrev_b64 v[8:9], 10, v[8:9]
	v_lshl_add_u64 v[6:7], v[152:153], 0, v[6:7]
	v_lshl_add_u64 v[8:9], v[152:153], 0, v[8:9]
	global_load_dwordx2 v[154:155], v[2:3], off
	global_load_dwordx2 v[156:157], v[4:5], off
	global_load_dwordx2 v[158:159], v[6:7], off
	global_load_dwordx2 v[160:161], v[8:9], off
	v_or_b32_e32 v4, 4, v150
	v_ashrrev_i32_e32 v5, 31, v4
	v_or_b32_e32 v6, 5, v150
	v_or_b32_e32 v8, 6, v150
	v_or_b32_e32 v10, 7, v150
	v_lshlrev_b64 v[4:5], 10, v[4:5]
	v_ashrrev_i32_e32 v7, 31, v6
	v_ashrrev_i32_e32 v9, 31, v8
	v_ashrrev_i32_e32 v11, 31, v10
	v_lshl_add_u64 v[4:5], v[152:153], 0, v[4:5]
	v_lshlrev_b64 v[6:7], 10, v[6:7]
	v_lshlrev_b64 v[8:9], 10, v[8:9]
	v_lshlrev_b64 v[10:11], 10, v[10:11]
	v_lshl_add_u64 v[6:7], v[152:153], 0, v[6:7]
	v_lshl_add_u64 v[8:9], v[152:153], 0, v[8:9]
	v_lshl_add_u64 v[10:11], v[152:153], 0, v[10:11]
	global_load_dwordx2 v[164:165], v[4:5], off
	global_load_dwordx2 v[166:167], v[6:7], off
	global_load_dwordx2 v[168:169], v[8:9], off
	global_load_dwordx2 v[172:173], v[10:11], off
	v_lshl_add_u64 v[162:163], v[2:3], 0, s[78:79]
	v_add_u32_e32 v2, 0x41, v150
	v_ashrrev_i32_e32 v3, 31, v2
	v_lshlrev_b64 v[2:3], 10, v[2:3]
	v_lshl_add_u64 v[170:171], v[152:153], 0, v[2:3]
	v_add_u32_e32 v2, 0x42, v150
	v_ashrrev_i32_e32 v3, 31, v2
	v_lshlrev_b64 v[2:3], 10, v[2:3]
	v_lshl_add_u64 v[174:175], v[152:153], 0, v[2:3]
	v_add_u32_e32 v2, 0x43, v150
	v_ashrrev_i32_e32 v3, 31, v2
	v_lshlrev_b64 v[2:3], 10, v[2:3]
	v_lshl_add_u64 v[176:177], v[152:153], 0, v[2:3]
	v_add_u32_e32 v2, 0x44, v150
	v_ashrrev_i32_e32 v3, 31, v2
	v_lshlrev_b64 v[2:3], 10, v[2:3]
	v_lshl_add_u64 v[178:179], v[152:153], 0, v[2:3]
	v_add_u32_e32 v2, 0x45, v150
	v_ashrrev_i32_e32 v3, 31, v2
	v_lshlrev_b64 v[2:3], 10, v[2:3]
	v_lshl_add_u64 v[180:181], v[152:153], 0, v[2:3]
	v_add_u32_e32 v2, 0x46, v150
	v_ashrrev_i32_e32 v3, 31, v2
	v_lshlrev_b64 v[2:3], 10, v[2:3]
	v_lshl_add_u64 v[182:183], v[152:153], 0, v[2:3]
	v_add_u32_e32 v2, 0x47, v150
	v_ashrrev_i32_e32 v3, 31, v2
	v_lshlrev_b64 v[2:3], 10, v[2:3]
	s_movk_i32 s4, 0x220
	v_mov_b32_e32 v46, 0
	v_lshlrev_b32_e32 v148, 2, v149
	v_add_u32_e32 v98, 32, v150
	v_lshl_add_u64 v[184:185], v[152:153], 0, v[2:3]
	v_mad_u32_u24 v213, v149, s4, 0
	s_mov_b32 s20, 0
	s_mov_b64 s[10:11], -1
	v_mov_b32_e32 v47, v46
	v_mov_b32_e32 v48, v46
	v_mov_b32_e32 v49, v46
	v_mov_b32_e32 v54, v46
	v_mov_b32_e32 v55, v46
	v_mov_b32_e32 v56, v46
	v_mov_b32_e32 v57, v46
	v_mov_b32_e32 v58, v46
	v_mov_b32_e32 v59, v46
	v_mov_b32_e32 v60, v46
	v_mov_b32_e32 v61, v46
	v_mov_b32_e32 v62, v46
	v_mov_b32_e32 v63, v46
	v_mov_b32_e32 v64, v46
	v_mov_b32_e32 v65, v46
	v_mov_b32_e32 v34, v46
	v_mov_b32_e32 v35, v46
	v_mov_b32_e32 v36, v46
	v_mov_b32_e32 v37, v46
	v_mov_b32_e32 v38, v46
	v_mov_b32_e32 v39, v46
	v_mov_b32_e32 v40, v46
	v_mov_b32_e32 v41, v46
	v_mov_b32_e32 v42, v46
	v_mov_b32_e32 v43, v46
	v_mov_b32_e32 v44, v46
	v_mov_b32_e32 v45, v46
	v_mov_b32_e32 v50, v46
	v_mov_b32_e32 v51, v46
	v_mov_b32_e32 v52, v46
	v_mov_b32_e32 v53, v46
	v_mov_b32_e32 v82, v46
	v_mov_b32_e32 v83, v46
	v_mov_b32_e32 v84, v46
	v_mov_b32_e32 v85, v46
	v_mov_b32_e32 v86, v46
	v_mov_b32_e32 v87, v46
	v_mov_b32_e32 v88, v46
	v_mov_b32_e32 v89, v46
	v_mov_b32_e32 v90, v46
	v_mov_b32_e32 v91, v46
	v_mov_b32_e32 v92, v46
	v_mov_b32_e32 v93, v46
	v_mov_b32_e32 v94, v46
	v_mov_b32_e32 v95, v46
	v_mov_b32_e32 v96, v46
	v_mov_b32_e32 v97, v46
	v_mov_b32_e32 v66, v46
	v_mov_b32_e32 v67, v46
	v_mov_b32_e32 v68, v46
	v_mov_b32_e32 v69, v46
	v_mov_b32_e32 v70, v46
	v_mov_b32_e32 v71, v46
	v_mov_b32_e32 v72, v46
	v_mov_b32_e32 v73, v46
	v_mov_b32_e32 v74, v46
	v_mov_b32_e32 v75, v46
	v_mov_b32_e32 v76, v46
	v_mov_b32_e32 v77, v46
	v_mov_b32_e32 v78, v46
	v_mov_b32_e32 v79, v46
	v_mov_b32_e32 v80, v46
	v_mov_b32_e32 v81, v46
	v_mov_b32_e32 v18, v46
	v_mov_b32_e32 v19, v46
	v_mov_b32_e32 v20, v46
	v_mov_b32_e32 v21, v46
	v_mov_b32_e32 v22, v46
	v_mov_b32_e32 v23, v46
	v_mov_b32_e32 v24, v46
	v_mov_b32_e32 v25, v46
	v_mov_b32_e32 v26, v46
	v_mov_b32_e32 v27, v46
	v_mov_b32_e32 v28, v46
	v_mov_b32_e32 v29, v46
	v_mov_b32_e32 v30, v46
	v_mov_b32_e32 v31, v46
	v_mov_b32_e32 v32, v46
	v_mov_b32_e32 v33, v46
	v_mov_b32_e32 v14, v46
	v_mov_b32_e32 v15, v46
	v_mov_b32_e32 v16, v46
	v_mov_b32_e32 v17, v46
	v_mov_b32_e32 v10, v46
	v_mov_b32_e32 v11, v46
	v_mov_b32_e32 v12, v46
	v_mov_b32_e32 v13, v46
	v_mov_b32_e32 v6, v46
	v_mov_b32_e32 v7, v46
	v_mov_b32_e32 v8, v46
	v_mov_b32_e32 v9, v46
	v_mov_b32_e32 v2, v46
	v_mov_b32_e32 v3, v46
	v_mov_b32_e32 v4, v46
	v_mov_b32_e32 v5, v46
	v_mov_b32_e32 v100, v46
	v_mov_b32_e32 v101, v46
	v_mov_b32_e32 v102, v46
	v_mov_b32_e32 v103, v46
	v_mov_b32_e32 v104, v46
	v_mov_b32_e32 v105, v46
	v_mov_b32_e32 v106, v46
	v_mov_b32_e32 v107, v46
	v_mov_b32_e32 v108, v46
	v_mov_b32_e32 v109, v46
	v_mov_b32_e32 v110, v46
	v_mov_b32_e32 v111, v46
	v_mov_b32_e32 v112, v46
	v_mov_b32_e32 v113, v46
	v_mov_b32_e32 v114, v46
	v_mov_b32_e32 v115, v46
	v_mov_b32_e32 v116, v46
	v_mov_b32_e32 v117, v46
	v_mov_b32_e32 v118, v46
	v_mov_b32_e32 v119, v46
	v_mov_b32_e32 v120, v46
	v_mov_b32_e32 v121, v46
	v_mov_b32_e32 v122, v46
	v_mov_b32_e32 v123, v46
	v_mov_b32_e32 v124, v46
	v_mov_b32_e32 v125, v46
	v_mov_b32_e32 v126, v46
	v_mov_b32_e32 v127, v46
	v_mov_b32_e32 v128, v46
	v_mov_b32_e32 v129, v46
	v_mov_b32_e32 v130, v46
	v_mov_b32_e32 v131, v46
	s_branch .LBB0_673

.LBB0_708:
	s_mov_b64 s[10:11], 0
	s_cmpk_gt_i32 s40, 0x45f
	s_mov_b64 s[14:15], 0
	s_cbranch_scc1 .LBB0_745
	s_sub_i32 s0, s40, 64
	s_lshr_b32 s0, s0, 3
	s_mul_hi_u32 s1, s0, 0x1f07c1f1
	s_lshr_b32 s1, s1, 2
	s_mul_i32 s1, s1, 33
	s_sub_i32 s30, s0, s1
	v_mov_b32_e32 v212, v210
	s_lshl_b32 s0, s30, 17
	v_readlane_b32 s1, v254, 25
	s_add_u32 s0, s1, s0
	v_ashrrev_i32_e32 v211, 4, v212
	v_readlane_b32 s1, v254, 26
	s_addc_u32 s1, s1, 0
	v_lshlrev_b32_e32 v150, 3, v211
	v_and_b32_e32 v149, 15, v212
	s_add_u32 s0, s0, s21
	v_or_b32_e32 v4, 1, v150
	s_addc_u32 s1, s1, 0
	v_lshlrev_b32_e32 v98, 3, v149
	v_ashrrev_i32_e32 v151, 31, v150
	v_ashrrev_i32_e32 v5, 31, v4
	v_or_b32_e32 v6, 2, v150
	v_or_b32_e32 v8, 3, v150
	v_lshl_add_u64 v[152:153], s[0:1], 0, v[98:99]
	v_lshlrev_b32_e32 v231, 10, v210
	global_load_dword v197, v231, s[0:1]
	v_add_u32_e32 v231, 0x10000, v231
	global_load_dword v197, v231, s[0:1]
	v_lshlrev_b64 v[2:3], 10, v[150:151]
	v_lshlrev_b64 v[4:5], 10, v[4:5]
	v_ashrrev_i32_e32 v7, 31, v6
	v_ashrrev_i32_e32 v9, 31, v8
	v_lshl_add_u64 v[2:3], v[152:153], 0, v[2:3]
	v_lshl_add_u64 v[4:5], v[152:153], 0, v[4:5]
	v_lshlrev_b64 v[6:7], 10, v[6:7]
	v_lshlrev_b64 v[8:9], 10, v[8:9]
	v_lshl_add_u64 v[6:7], v[152:153], 0, v[6:7]
	v_lshl_add_u64 v[8:9], v[152:153], 0, v[8:9]
	global_load_dwordx2 v[154:155], v[2:3], off
	global_load_dwordx2 v[156:157], v[4:5], off
	global_load_dwordx2 v[158:159], v[6:7], off
	global_load_dwordx2 v[160:161], v[8:9], off
	v_or_b32_e32 v4, 4, v150
	v_ashrrev_i32_e32 v5, 31, v4
	v_or_b32_e32 v6, 5, v150
	v_or_b32_e32 v8, 6, v150
	v_or_b32_e32 v10, 7, v150
	v_lshlrev_b64 v[4:5], 10, v[4:5]
	v_ashrrev_i32_e32 v7, 31, v6
	v_ashrrev_i32_e32 v9, 31, v8
	v_ashrrev_i32_e32 v11, 31, v10
	v_lshl_add_u64 v[4:5], v[152:153], 0, v[4:5]
	v_lshlrev_b64 v[6:7], 10, v[6:7]
	v_lshlrev_b64 v[8:9], 10, v[8:9]
	v_lshlrev_b64 v[10:11], 10, v[10:11]
	v_lshl_add_u64 v[6:7], v[152:153], 0, v[6:7]
	v_lshl_add_u64 v[8:9], v[152:153], 0, v[8:9]
	v_lshl_add_u64 v[10:11], v[152:153], 0, v[10:11]
	global_load_dwordx2 v[164:165], v[4:5], off
	global_load_dwordx2 v[166:167], v[6:7], off
	global_load_dwordx2 v[168:169], v[8:9], off
	global_load_dwordx2 v[172:173], v[10:11], off
	v_lshl_add_u64 v[162:163], v[2:3], 0, s[78:79]
	v_add_u32_e32 v2, 0x41, v150
	v_ashrrev_i32_e32 v3, 31, v2
	v_lshlrev_b64 v[2:3], 10, v[2:3]
	v_lshl_add_u64 v[170:171], v[152:153], 0, v[2:3]
	v_add_u32_e32 v2, 0x42, v150
	v_ashrrev_i32_e32 v3, 31, v2
	v_lshlrev_b64 v[2:3], 10, v[2:3]
	v_lshl_add_u64 v[174:175], v[152:153], 0, v[2:3]
	v_add_u32_e32 v2, 0x43, v150
	v_ashrrev_i32_e32 v3, 31, v2
	v_lshlrev_b64 v[2:3], 10, v[2:3]
	v_lshl_add_u64 v[176:177], v[152:153], 0, v[2:3]
	v_add_u32_e32 v2, 0x44, v150
	v_ashrrev_i32_e32 v3, 31, v2
	v_lshlrev_b64 v[2:3], 10, v[2:3]
	v_lshl_add_u64 v[178:179], v[152:153], 0, v[2:3]
	v_add_u32_e32 v2, 0x45, v150
	v_ashrrev_i32_e32 v3, 31, v2
	v_lshlrev_b64 v[2:3], 10, v[2:3]
	v_lshl_add_u64 v[180:181], v[152:153], 0, v[2:3]
	v_add_u32_e32 v2, 0x46, v150
	v_ashrrev_i32_e32 v3, 31, v2
	v_lshlrev_b64 v[2:3], 10, v[2:3]
	v_lshl_add_u64 v[182:183], v[152:153], 0, v[2:3]
	v_add_u32_e32 v2, 0x47, v150
	v_ashrrev_i32_e32 v3, 31, v2
	v_lshlrev_b64 v[2:3], 10, v[2:3]
	s_movk_i32 s0, 0x220
	v_mov_b32_e32 v46, 0
	v_lshlrev_b32_e32 v148, 2, v149
	v_add_u32_e32 v98, 32, v150
	v_lshl_add_u64 v[184:185], v[152:153], 0, v[2:3]
	v_mad_u32_u24 v213, v149, s0, 0
	s_mov_b32 s31, 0
	s_mov_b64 s[0:1], -1
	v_mov_b32_e32 v47, v46
	v_mov_b32_e32 v48, v46
	v_mov_b32_e32 v49, v46
	v_mov_b32_e32 v54, v46
	v_mov_b32_e32 v55, v46
	v_mov_b32_e32 v56, v46
	v_mov_b32_e32 v57, v46
	v_mov_b32_e32 v58, v46
	v_mov_b32_e32 v59, v46
	v_mov_b32_e32 v60, v46
	v_mov_b32_e32 v61, v46
	v_mov_b32_e32 v62, v46
	v_mov_b32_e32 v63, v46
	v_mov_b32_e32 v64, v46
	v_mov_b32_e32 v65, v46
	v_mov_b32_e32 v34, v46
	v_mov_b32_e32 v35, v46
	v_mov_b32_e32 v36, v46
	v_mov_b32_e32 v37, v46
	v_mov_b32_e32 v38, v46
	v_mov_b32_e32 v39, v46
	v_mov_b32_e32 v40, v46
	v_mov_b32_e32 v41, v46
	v_mov_b32_e32 v42, v46
	v_mov_b32_e32 v43, v46
	v_mov_b32_e32 v44, v46
	v_mov_b32_e32 v45, v46
	v_mov_b32_e32 v50, v46
	v_mov_b32_e32 v51, v46
	v_mov_b32_e32 v52, v46
	v_mov_b32_e32 v53, v46
	v_mov_b32_e32 v82, v46
	v_mov_b32_e32 v83, v46
	v_mov_b32_e32 v84, v46
	v_mov_b32_e32 v85, v46
	v_mov_b32_e32 v86, v46
	v_mov_b32_e32 v87, v46
	v_mov_b32_e32 v88, v46
	v_mov_b32_e32 v89, v46
	v_mov_b32_e32 v90, v46
	v_mov_b32_e32 v91, v46
	v_mov_b32_e32 v92, v46
	v_mov_b32_e32 v93, v46
	v_mov_b32_e32 v94, v46
	v_mov_b32_e32 v95, v46
	v_mov_b32_e32 v96, v46
	v_mov_b32_e32 v97, v46
	v_mov_b32_e32 v66, v46
	v_mov_b32_e32 v67, v46
	v_mov_b32_e32 v68, v46
	v_mov_b32_e32 v69, v46
	v_mov_b32_e32 v70, v46
	v_mov_b32_e32 v71, v46
	v_mov_b32_e32 v72, v46
	v_mov_b32_e32 v73, v46
	v_mov_b32_e32 v74, v46
	v_mov_b32_e32 v75, v46
	v_mov_b32_e32 v76, v46
	v_mov_b32_e32 v77, v46
	v_mov_b32_e32 v78, v46
	v_mov_b32_e32 v79, v46
	v_mov_b32_e32 v80, v46
	v_mov_b32_e32 v81, v46
	v_mov_b32_e32 v18, v46
	v_mov_b32_e32 v19, v46
	v_mov_b32_e32 v20, v46
	v_mov_b32_e32 v21, v46
	v_mov_b32_e32 v22, v46
	v_mov_b32_e32 v23, v46
	v_mov_b32_e32 v24, v46
	v_mov_b32_e32 v25, v46
	v_mov_b32_e32 v26, v46
	v_mov_b32_e32 v27, v46
	v_mov_b32_e32 v28, v46
	v_mov_b32_e32 v29, v46
	v_mov_b32_e32 v30, v46
	v_mov_b32_e32 v31, v46
	v_mov_b32_e32 v32, v46
	v_mov_b32_e32 v33, v46
	v_mov_b32_e32 v14, v46
	v_mov_b32_e32 v15, v46
	v_mov_b32_e32 v16, v46
	v_mov_b32_e32 v17, v46
	v_mov_b32_e32 v10, v46
	v_mov_b32_e32 v11, v46
	v_mov_b32_e32 v12, v46
	v_mov_b32_e32 v13, v46
	v_mov_b32_e32 v6, v46
	v_mov_b32_e32 v7, v46
	v_mov_b32_e32 v8, v46
	v_mov_b32_e32 v9, v46
	v_mov_b32_e32 v2, v46
	v_mov_b32_e32 v3, v46
	v_mov_b32_e32 v4, v46
	v_mov_b32_e32 v5, v46
	v_mov_b32_e32 v100, v46
	v_mov_b32_e32 v101, v46
	v_mov_b32_e32 v102, v46
	v_mov_b32_e32 v103, v46
	v_mov_b32_e32 v104, v46
	v_mov_b32_e32 v105, v46
	v_mov_b32_e32 v106, v46
	v_mov_b32_e32 v107, v46
	v_mov_b32_e32 v108, v46
	v_mov_b32_e32 v109, v46
	v_mov_b32_e32 v110, v46
	v_mov_b32_e32 v111, v46
	v_mov_b32_e32 v112, v46
	v_mov_b32_e32 v113, v46
	v_mov_b32_e32 v114, v46
	v_mov_b32_e32 v115, v46
	v_mov_b32_e32 v116, v46
	v_mov_b32_e32 v117, v46
	v_mov_b32_e32 v118, v46
	v_mov_b32_e32 v119, v46
	v_mov_b32_e32 v120, v46
	v_mov_b32_e32 v121, v46
	v_mov_b32_e32 v122, v46
	v_mov_b32_e32 v123, v46
	v_mov_b32_e32 v124, v46
	v_mov_b32_e32 v125, v46
	v_mov_b32_e32 v126, v46
	v_mov_b32_e32 v127, v46
	v_mov_b32_e32 v128, v46
	v_mov_b32_e32 v129, v46
	v_mov_b32_e32 v130, v46
	v_mov_b32_e32 v131, v46
	s_branch .LBB0_711

.LBB0_745:
	s_and_b64 vcc, exec, s[10:11]
	s_cbranch_vccz .LBB0_782
	s_ashr_i32 s0, s40, 4
	s_mul_hi_i32 s1, s0, 0x3e0f83e1
	s_lshr_b32 s4, s1, 31
	s_ashr_i32 s1, s1, 3
	s_add_i32 s1, s1, s4
	s_mul_i32 s4, s1, 33
	s_sub_i32 s0, s0, s4
	s_lshl_b32 s10, s1, 13
	s_bfe_u32 s18, s18, 0x30006
	s_ashr_i32 s11, s10, 31
	s_ashr_i32 s1, s0, 31
	s_lshl_b64 s[12:13], s[10:11], 11
	s_lshl_b64 s[20:21], s[0:1], 18
	s_lshl_b32 s11, s18, 6
	v_readlane_b32 s1, v254, 17
	s_add_u32 s1, s1, s12
	v_readlane_b32 s4, v254, 18
	s_addc_u32 s4, s4, s13
	s_add_u32 s1, s1, s20
	s_addc_u32 s4, s4, s21
	v_ashrrev_i32_e32 v186, 4, v210
	s_lshl_b32 s5, s18, 7
	v_and_b32_e32 v149, 15, v210
	s_add_u32 s30, s1, s5
	v_lshlrev_b32_e32 v150, 3, v186
	s_addc_u32 s31, s4, 0
	v_lshlrev_b32_e32 v98, 3, v149
	v_ashrrev_i32_e32 v151, 31, v150
	s_waitcnt vmcnt(0)
	v_or_b32_e32 v8, 1, v150
	v_or_b32_e32 v10, 2, v150
	v_or_b32_e32 v12, 3, v150
	v_lshl_add_u64 v[2:3], s[30:31], 0, v[98:99]
	v_lshlrev_b32_e32 v231, 10, v210
	global_load_dword v197, v231, s[30:31]
	v_add_u32_e32 v231, 0x10000, v231
	global_load_dword v197, v231, s[30:31]
	v_add_u32_e32 v231, 0x10000, v231
	global_load_dword v197, v231, s[30:31]
	v_add_u32_e32 v231, 0x10000, v231
	global_load_dword v197, v231, s[30:31]
	v_lshlrev_b64 v[4:5], 10, v[150:151]
	v_ashrrev_i32_e32 v9, 31, v8
	v_ashrrev_i32_e32 v11, 31, v10
	v_ashrrev_i32_e32 v13, 31, v12
	v_lshl_add_u64 v[6:7], v[2:3], 0, v[4:5]
	v_lshlrev_b64 v[8:9], 10, v[8:9]
	v_lshlrev_b64 v[10:11], 10, v[10:11]
	v_lshlrev_b64 v[12:13], 10, v[12:13]
	v_lshl_add_u64 v[8:9], v[2:3], 0, v[8:9]
	v_lshl_add_u64 v[10:11], v[2:3], 0, v[10:11]
	v_lshl_add_u64 v[12:13], v[2:3], 0, v[12:13]
	global_load_dwordx2 v[152:153], v[6:7], off
	global_load_dwordx2 v[154:155], v[8:9], off
	global_load_dwordx2 v[156:157], v[10:11], off
	global_load_dwordx2 v[158:159], v[12:13], off
	v_or_b32_e32 v6, 4, v150
	v_ashrrev_i32_e32 v7, 31, v6
	v_or_b32_e32 v8, 5, v150
	v_or_b32_e32 v10, 6, v150
	v_or_b32_e32 v12, 7, v150
	v_lshlrev_b64 v[6:7], 10, v[6:7]
	v_ashrrev_i32_e32 v9, 31, v8
	v_ashrrev_i32_e32 v11, 31, v10
	v_ashrrev_i32_e32 v13, 31, v12
	v_lshl_add_u64 v[6:7], v[2:3], 0, v[6:7]
	v_lshlrev_b64 v[8:9], 10, v[8:9]
	v_lshlrev_b64 v[10:11], 10, v[10:11]
	v_lshlrev_b64 v[12:13], 10, v[12:13]
	v_lshl_add_u64 v[8:9], v[2:3], 0, v[8:9]
	v_lshl_add_u64 v[10:11], v[2:3], 0, v[10:11]
	v_lshl_add_u64 v[2:3], v[2:3], 0, v[12:13]
	global_load_dwordx2 v[160:161], v[6:7], off
	global_load_dwordx2 v[162:163], v[8:9], off
	global_load_dwordx2 v[164:165], v[10:11], off
	global_load_dwordx2 v[166:167], v[2:3], off
	s_lshl_b32 s1, s40, 3
	s_and_b32 s1, s1, 64
	s_add_u32 s12, s20, s12
	v_or_b32_e32 v2, s1, v149
	s_movk_i32 s4, 0x110
	s_addc_u32 s13, s21, s13
	v_mad_u32_u24 v187, v2, s4, 0
	v_lshl_add_u64 v[2:3], s[12:13], 0, v[4:5]
	v_or3_b32 v2, v2, s5, v98
	v_readlane_b32 s4, v255, 17
	v_readlane_b32 s5, v255, 18
	v_mov_b32_e32 v34, 0
	v_lshlrev_b32_e32 v148, 2, v149
	v_lshl_add_u64 v[168:169], s[4:5], 0, v[2:3]
	s_mov_b32 s20, 0
	v_mov_b32_e32 v98, v150
	v_mov_b32_e32 v35, v34
	v_mov_b32_e32 v36, v34
	v_mov_b32_e32 v37, v34
	v_mov_b32_e32 v38, v34
	v_mov_b32_e32 v39, v34
	v_mov_b32_e32 v40, v34
	v_mov_b32_e32 v41, v34
	v_mov_b32_e32 v42, v34
	v_mov_b32_e32 v43, v34
	v_mov_b32_e32 v44, v34
	v_mov_b32_e32 v45, v34
	v_mov_b32_e32 v46, v34
	v_mov_b32_e32 v47, v34
	v_mov_b32_e32 v48, v34
	v_mov_b32_e32 v49, v34
	v_mov_b32_e32 v18, v34
	v_mov_b32_e32 v19, v34
	v_mov_b32_e32 v20, v34
	v_mov_b32_e32 v21, v34
	v_mov_b32_e32 v22, v34
	v_mov_b32_e32 v23, v34
	v_mov_b32_e32 v24, v34
	v_mov_b32_e32 v25, v34
	v_mov_b32_e32 v26, v34
	v_mov_b32_e32 v27, v34
	v_mov_b32_e32 v28, v34
	v_mov_b32_e32 v29, v34
	v_mov_b32_e32 v30, v34
	v_mov_b32_e32 v31, v34
	v_mov_b32_e32 v32, v34
	v_mov_b32_e32 v33, v34
	v_mov_b32_e32 v82, v34
	v_mov_b32_e32 v83, v34
	v_mov_b32_e32 v84, v34
	v_mov_b32_e32 v85, v34
	v_mov_b32_e32 v86, v34
	v_mov_b32_e32 v87, v34
	v_mov_b32_e32 v88, v34
	v_mov_b32_e32 v89, v34
	v_mov_b32_e32 v90, v34
	v_mov_b32_e32 v91, v34
	v_mov_b32_e32 v92, v34
	v_mov_b32_e32 v93, v34
	v_mov_b32_e32 v94, v34
	v_mov_b32_e32 v95, v34
	v_mov_b32_e32 v96, v34
	v_mov_b32_e32 v97, v34
	v_mov_b32_e32 v66, v34
	v_mov_b32_e32 v67, v34
	v_mov_b32_e32 v68, v34
	v_mov_b32_e32 v69, v34
	v_mov_b32_e32 v70, v34
	v_mov_b32_e32 v71, v34
	v_mov_b32_e32 v72, v34
	v_mov_b32_e32 v73, v34
	v_mov_b32_e32 v74, v34
	v_mov_b32_e32 v75, v34
	v_mov_b32_e32 v76, v34
	v_mov_b32_e32 v77, v34
	v_mov_b32_e32 v78, v34
	v_mov_b32_e32 v79, v34
	v_mov_b32_e32 v80, v34
	v_mov_b32_e32 v81, v34
	v_mov_b32_e32 v50, v34
	v_mov_b32_e32 v51, v34
	v_mov_b32_e32 v52, v34
	v_mov_b32_e32 v53, v34
	v_mov_b32_e32 v54, v34
	v_mov_b32_e32 v55, v34
	v_mov_b32_e32 v56, v34
	v_mov_b32_e32 v57, v34
	v_mov_b32_e32 v58, v34
	v_mov_b32_e32 v59, v34
	v_mov_b32_e32 v60, v34
	v_mov_b32_e32 v61, v34
	v_mov_b32_e32 v62, v34
	v_mov_b32_e32 v63, v34
	v_mov_b32_e32 v64, v34
	v_mov_b32_e32 v65, v34
	v_mov_b32_e32 v14, v34
	v_mov_b32_e32 v15, v34
	v_mov_b32_e32 v16, v34
	v_mov_b32_e32 v17, v34
	v_mov_b32_e32 v2, v34
	v_mov_b32_e32 v3, v34
	v_mov_b32_e32 v4, v34
	v_mov_b32_e32 v5, v34
	v_mov_b32_e32 v6, v34
	v_mov_b32_e32 v7, v34
	v_mov_b32_e32 v8, v34
	v_mov_b32_e32 v9, v34
	v_mov_b32_e32 v10, v34
	v_mov_b32_e32 v11, v34
	v_mov_b32_e32 v12, v34
	v_mov_b32_e32 v13, v34
	v_mov_b32_e32 v100, v34
	v_mov_b32_e32 v101, v34
	v_mov_b32_e32 v102, v34
	v_mov_b32_e32 v103, v34
	v_mov_b32_e32 v104, v34
	v_mov_b32_e32 v105, v34
	v_mov_b32_e32 v106, v34
	v_mov_b32_e32 v107, v34
	v_mov_b32_e32 v108, v34
	v_mov_b32_e32 v109, v34
	v_mov_b32_e32 v110, v34
	v_mov_b32_e32 v111, v34
	v_mov_b32_e32 v112, v34
	v_mov_b32_e32 v113, v34
	v_mov_b32_e32 v114, v34
	v_mov_b32_e32 v115, v34
	v_mov_b32_e32 v116, v34
	v_mov_b32_e32 v117, v34
	v_mov_b32_e32 v118, v34
	v_mov_b32_e32 v119, v34
	v_mov_b32_e32 v120, v34
	v_mov_b32_e32 v121, v34
	v_mov_b32_e32 v122, v34
	v_mov_b32_e32 v123, v34
	v_mov_b32_e32 v124, v34
	v_mov_b32_e32 v125, v34
	v_mov_b32_e32 v126, v34
	v_mov_b32_e32 v127, v34
	v_mov_b32_e32 v128, v34
	v_mov_b32_e32 v129, v34
	v_mov_b32_e32 v130, v34
	v_mov_b32_e32 v131, v34
	s_branch .LBB0_748
